# G2b: gMLP unit load de-serialisation (top-of-unit prefetch of v chunks, LN gain/bias, Wtril fragments, u chunks; original loads become moves) with the prefetch wait before the first Wtril use
# baseline (speedup 1.0000x reference)
; __device__ __forceinline__ float bf_lo(unsigned w) { return __uint_as_float(w << 16); }
; __device__ __forceinline__ float bf_hi(unsigned w) { return __uint_as_float(w & 0xffff0000u); }
; __device__ __forceinline__ bf16_t f2bf(float f) { return (bf16_t)(cvt_pk_bf16(f, 0.f) & 0xffffu); }
; __global__ void __launch_bounds__(NTHR, 2) mega_fwd(Args a) {
;     ...
;                     const int tok = tid >> 2, cq = (tid & 3) * 32; const float mean = st[2 * tok], rstd = st[2 * tok + 1];
;                     const bf16_t* vp = PB + ((size_t)(16 + gi) * T + r0 + tok) * 128 + cq;
; #pragma unroll
;                     for (int i = 0; i < 4; ++i) { const u32x4 w = *(const u32x4*)(vp + 8 * i);
; #pragma unroll
;                         for (int j = 0; j < 4; ++j) { const int c = cq + 8 * i + 2 * j;
;                             const float x0 = gelu_tanh(bf_lo(w[j])), x1 = gelu_tanh(bf_hi(w[j]));
;                             vT[c * 136 + tok] = f2bf((x0 - mean) * rstd * lng[gi * 128 + c] + lnb[gi * 128 + c]);
;                             vT[(c + 1) * 136 + tok] = f2bf((x1 - mean) * rstd * lng[gi * 128 + c + 1] + lnb[gi * 128 + c + 1]); } }
;     ...
;                     const bf16_t* wrow = wtril + ((size_t)(l * 4 + gi) * 128 + 16 * wave + (lane & 15)) * 128 + 8 * (lane >> 4);
; #pragma unroll
;                     for (int kk = 0; kk < 4; ++kk) { const bf16x8 av = *(const bf16x8*)(wrow + kk * 32);
; #pragma unroll
;                         for (int ct = 0; ct < 8; ++ct) { const bf16x8 bv = *(const bf16x8*)(vT + (ct * 16 + (lane & 15)) * 136 + kk * 32 + 8 * (lane >> 4));
;                             acc[ct] = __builtin_amdgcn_mfma_f32_16x16x32_bf16(av, bv, acc[ct], 0, 0, 0); } }
; #pragma unroll
;                     for (int j = 0; j < 4; ++j) { const int t = 16 * wave + 4 * (lane >> 4) + j; const float bt = bs[gi * 128 + t];
; #pragma unroll
;                         for (int ct = 0; ct < 8; ++ct) svL[t * 132 + ct * 16 + (lane & 15)] = acc[ct][j] + bt; }
;                 }
;                 __syncthreads();
;                 {
;                     const int c0 = (tid & 15) * 8;
; #pragma unroll
;                     for (int i = 0; i < 4; ++i) { const int t = 32 * i + (tid >> 4);
;                         const u32x4 uw = *(const u32x4*)(PB + ((size_t)(12 + gi) * T + r0 + t) * 128 + c0);
.LBB0_518:
	s_or_b64 exec, exec, s[14:15]
	s_and_b32 s26, s22, 3
	s_lshl_b32 s14, s26, 14
	s_or_b32 s10, s14, 0x40000
	s_ashr_i32 s15, s23, 31
	s_add_u32 s34, s10, s23
	s_addc_u32 s35, 0, s15
	v_lshl_add_u64 v[4:5], s[34:35], 0, v[36:37]
	v_lshlrev_b64 v[4:5], 8, v[4:5]
	v_lshl_add_u64 v[10:11], v[38:39], 0, v[4:5]
	s_waitcnt lgkmcnt(0)
	s_barrier
	global_load_dwordx4 v[4:7], v[10:11], off
	ds_read_b64 v[8:9], v57 offset:40960
	s_lshl_b32 s27, s26, 7
	s_or_b32 s30, s27, s16
	s_or_b32 s10, s14, 0x30000
	s_add_u32 s14, s10, s23
	s_addc_u32 s15, 0, s15
	s_add_i32 s22, s22, s13
	s_add_i32 s17, s17, s33
	global_load_dwordx4 v[100:103], v[10:11], off offset:16
	global_load_dwordx4 v[104:107], v[10:11], off offset:32
	global_load_dwordx4 v[108:111], v[10:11], off offset:48
	v_or_b32_e32 v112, s27, v56
	v_lshlrev_b32_e32 v112, 2, v112
	global_load_dwordx4 v[116:119], v112, s[4:5]
	global_load_dwordx4 v[120:123], v112, s[4:5] offset:16
	global_load_dwordx4 v[124:127], v112, s[4:5] offset:32
	global_load_dwordx4 v[128:131], v112, s[4:5] offset:48
	global_load_dwordx4 v[132:135], v112, s[4:5] offset:64
	global_load_dwordx4 v[136:139], v112, s[4:5] offset:80
	global_load_dwordx4 v[140:143], v112, s[4:5] offset:96
	global_load_dwordx4 v[144:147], v112, s[4:5] offset:112
	global_load_dwordx4 v[148:151], v112, s[6:7]
	global_load_dwordx4 v[152:155], v112, s[6:7] offset:16
	global_load_dwordx4 v[156:159], v112, s[6:7] offset:32
	global_load_dwordx4 v[160:163], v112, s[6:7] offset:48
	global_load_dwordx4 v[164:167], v112, s[6:7] offset:64
	global_load_dwordx4 v[168:171], v112, s[6:7] offset:80
	global_load_dwordx4 v[172:175], v112, s[6:7] offset:96
	global_load_dwordx4 v[176:179], v112, s[6:7] offset:112
	s_waitcnt vmcnt(0)
	v_lshl_add_u64 v[114:115], v[40:41], 0, s[30:31]
	v_lshlrev_b64 v[114:115], 8, v[114:115]
	v_lshl_add_u64 v[114:115], v[42:43], 0, v[114:115]
	global_load_dwordx4 v[180:183], v[114:115], off
	global_load_dwordx4 v[184:187], v[114:115], off offset:64
	global_load_dwordx4 v[188:191], v[114:115], off offset:128
	global_load_dwordx4 v[192:195], v[114:115], off offset:192
	v_lshl_add_u64 v[214:215], s[14:15], 0, v[44:45]
	v_lshlrev_b64 v[214:215], 8, v[214:215]
	v_lshl_add_u64 v[214:215], v[46:47], 0, v[214:215]
	global_load_dwordx4 v[218:221], v[214:215], off
	v_lshl_add_u64 v[214:215], s[14:15], 0, v[48:49]
	v_lshlrev_b64 v[214:215], 8, v[214:215]
	v_lshl_add_u64 v[214:215], v[46:47], 0, v[214:215]
	global_load_dwordx4 v[222:225], v[214:215], off
	v_lshl_add_u64 v[214:215], s[14:15], 0, v[50:51]
	v_lshlrev_b64 v[214:215], 8, v[214:215]
	v_lshl_add_u64 v[214:215], v[46:47], 0, v[214:215]
	global_load_dwordx4 v[226:229], v[214:215], off
	v_lshl_add_u64 v[214:215], s[14:15], 0, v[52:53]
	v_lshlrev_b64 v[214:215], 8, v[214:215]
	v_lshl_add_u64 v[214:215], v[46:47], 0, v[214:215]
	global_load_dwordx4 v[230:233], v[214:215], off
	v_lshlrev_b32_e32 v12, 16, v4
	v_mul_f32_e32 v13, 0x3d372713, v12
	v_mul_f32_e32 v13, v13, v12
	v_fma_f32 v13, v13, v12, v12
	v_mul_f32_e32 v13, 0x3f4c422a, v13
	v_mul_f32_e32 v13, -2.0, v13
	v_mul_f32_e32 v13, 0x3fb8aa3b, v13
	v_exp_f32_e32 v13, v13
	v_and_b32_e32 v4, 0xffff0000, v4
	v_mul_f32_e32 v14, 0x3d372713, v4
	v_mul_f32_e32 v14, v14, v4
	v_add_f32_e32 v13, 1.0, v13
	v_rcp_f32_e32 v13, v13
	v_fma_f32 v14, v14, v4, v4
	v_mul_f32_e32 v14, 0x3f4c422a, v14
	v_mul_f32_e32 v14, -2.0, v14
	s_waitcnt lgkmcnt(0)
	v_fma_f32 v12, v13, v12, -v8
	v_mul_f32_e32 v13, v9, v12
	v_or_b32_e32 v12, s27, v56
	v_lshlrev_b32_e32 v12, 2, v12
	v_mov_b32_e32 v15, v116
	v_mov_b32_e32 v16, v148
	v_mul_f32_e32 v14, 0x3fb8aa3b, v14
	v_exp_f32_e32 v14, v14
	v_fmac_f32_e32 v16, v13, v15
	v_add_f32_e32 v14, 1.0, v14
	v_rcp_f32_e32 v14, v14
	v_cvt_pk_bf16_f32 v13, v16, v3
	ds_write_b16 v60, v13
	v_fma_f32 v4, v14, v4, -v8
	v_mov_b32_e32 v13, v117
	v_mov_b32_e32 v14, v149
	v_mul_f32_e32 v4, v9, v4
	v_fmac_f32_e32 v14, v4, v13
	v_cvt_pk_bf16_f32 v4, v14, v3
	ds_write_b16 v61, v4 offset:272
	v_lshlrev_b32_e32 v4, 16, v5
	v_mul_f32_e32 v13, 0x3d372713, v4
	v_mul_f32_e32 v13, v13, v4
	v_fma_f32 v13, v13, v4, v4
	v_mul_f32_e32 v13, 0x3f4c422a, v13
	v_mul_f32_e32 v13, -2.0, v13
	v_mul_f32_e32 v13, 0x3fb8aa3b, v13
	v_exp_f32_e32 v13, v13
	v_and_b32_e32 v5, 0xffff0000, v5
	v_mul_f32_e32 v14, 0x3d372713, v5
	v_mul_f32_e32 v14, v14, v5
	v_add_f32_e32 v13, 1.0, v13
	v_rcp_f32_e32 v13, v13
	v_fma_f32 v14, v14, v5, v5
	v_mul_f32_e32 v14, 0x3f4c422a, v14
	v_mul_f32_e32 v14, -2.0, v14
	v_fma_f32 v4, v13, v4, -v8
	v_mov_b32_e32 v13, v118
	v_mov_b32_e32 v15, v150
	v_mul_f32_e32 v14, 0x3fb8aa3b, v14
	v_exp_f32_e32 v14, v14
	v_mul_f32_e32 v4, v9, v4
	v_add_f32_e32 v14, 1.0, v14
	v_rcp_f32_e32 v14, v14
	v_fmac_f32_e32 v15, v4, v13
	v_cvt_pk_bf16_f32 v4, v15, v3
	ds_write_b16 v61, v4 offset:544
	v_fma_f32 v4, v14, v5, -v8
	v_mov_b32_e32 v5, v119
	v_mov_b32_e32 v13, v151
	v_mul_f32_e32 v4, v9, v4
	v_fmac_f32_e32 v13, v4, v5
	v_cvt_pk_bf16_f32 v4, v13, v3
	ds_write_b16 v62, v4 offset:272
	v_lshlrev_b32_e32 v4, 16, v6
	v_mul_f32_e32 v5, 0x3d372713, v4
	v_mul_f32_e32 v5, v5, v4
	v_fma_f32 v5, v5, v4, v4
	v_mul_f32_e32 v5, 0x3f4c422a, v5
	v_mul_f32_e32 v5, -2.0, v5
	v_mul_f32_e32 v5, 0x3fb8aa3b, v5
	v_exp_f32_e32 v5, v5
	v_and_b32_e32 v6, 0xffff0000, v6
	v_mul_f32_e32 v13, 0x3d372713, v6
	v_mul_f32_e32 v13, v13, v6
	v_add_f32_e32 v5, 1.0, v5
	v_rcp_f32_e32 v5, v5
	v_fma_f32 v13, v13, v6, v6
	v_mul_f32_e32 v13, 0x3f4c422a, v13
	v_mul_f32_e32 v13, -2.0, v13
	v_fma_f32 v4, v5, v4, -v8
	v_mov_b32_e32 v5, v120
	v_mov_b32_e32 v14, v152
	v_mul_f32_e32 v13, 0x3fb8aa3b, v13
	v_exp_f32_e32 v13, v13
	v_mul_f32_e32 v4, v9, v4
	v_add_f32_e32 v13, 1.0, v13
	v_rcp_f32_e32 v13, v13
; __device__ __forceinline__ float bf_lo(unsigned w) { return __uint_as_float(w << 16); }
; __device__ __forceinline__ float bf_hi(unsigned w) { return __uint_as_float(w & 0xffff0000u); }
; __device__ __forceinline__ bf16_t f2bf(float f) { return (bf16_t)(cvt_pk_bf16(f, 0.f) & 0xffffu); }
; __global__ void __launch_bounds__(NTHR, 2) mega_fwd(Args a) {
;     ...
;                     for (int i = 0; i < 4; ++i) { const u32x4 w = *(const u32x4*)(vp + 8 * i);
; #pragma unroll
;                         for (int j = 0; j < 4; ++j) { const int c = cq + 8 * i + 2 * j;
;                             const float x0 = gelu_tanh(bf_lo(w[j])), x1 = gelu_tanh(bf_hi(w[j]));
;                             vT[c * 136 + tok] = f2bf((x0 - mean) * rstd * lng[gi * 128 + c] + lnb[gi * 128 + c]);
;                             vT[(c + 1) * 136 + tok] = f2bf((x1 - mean) * rstd * lng[gi * 128 + c + 1] + lnb[gi * 128 + c + 1]); } }
	v_fmac_f32_e32 v14, v4, v5
	v_cvt_pk_bf16_f32 v4, v14, v3
	ds_write_b16 v62, v4 offset:544
	v_fma_f32 v4, v13, v6, -v8
	v_mov_b32_e32 v5, v121
	v_mov_b32_e32 v6, v153
	v_mul_f32_e32 v4, v9, v4
	v_fmac_f32_e32 v6, v4, v5
	v_cvt_pk_bf16_f32 v4, v6, v3
	ds_write_b16 v63, v4 offset:272
	v_lshlrev_b32_e32 v4, 16, v7
	v_mul_f32_e32 v5, 0x3d372713, v4
	v_mul_f32_e32 v5, v5, v4
	v_fma_f32 v5, v5, v4, v4
	v_mul_f32_e32 v5, 0x3f4c422a, v5
	v_mul_f32_e32 v5, -2.0, v5
	v_mul_f32_e32 v5, 0x3fb8aa3b, v5
	v_exp_f32_e32 v5, v5
	v_and_b32_e32 v6, 0xffff0000, v7
	v_mul_f32_e32 v7, 0x3d372713, v6
	v_mul_f32_e32 v7, v7, v6
	v_add_f32_e32 v5, 1.0, v5
	v_rcp_f32_e32 v5, v5
	v_fma_f32 v7, v7, v6, v6
	v_mul_f32_e32 v7, 0x3f4c422a, v7
	v_mul_f32_e32 v7, -2.0, v7
	v_fma_f32 v4, v5, v4, -v8
	v_mov_b32_e32 v5, v122
	v_mov_b32_e32 v13, v154
	v_mul_f32_e32 v7, 0x3fb8aa3b, v7
	v_exp_f32_e32 v7, v7
	v_mul_f32_e32 v4, v9, v4
	v_add_f32_e32 v7, 1.0, v7
	v_rcp_f32_e32 v7, v7
	v_fmac_f32_e32 v13, v4, v5
	v_cvt_pk_bf16_f32 v4, v13, v3
	ds_write_b16 v63, v4 offset:544
	v_fma_f32 v4, v7, v6, -v8
	v_mov_b32_e32 v5, v123
	v_mov_b32_e32 v6, v155
	v_mul_f32_e32 v4, v9, v4
	v_fmac_f32_e32 v6, v4, v5
	v_cvt_pk_bf16_f32 v4, v6, v3
	ds_write_b16 v64, v4 offset:272
	v_mov_b64_e32 v[4:5], v[100:101]
	v_mov_b64_e32 v[6:7], v[102:103]
	v_lshlrev_b32_e32 v13, 16, v4
	v_mul_f32_e32 v14, 0x3d372713, v13
	v_mul_f32_e32 v14, v14, v13
	v_fma_f32 v14, v14, v13, v13
	v_mul_f32_e32 v14, 0x3f4c422a, v14
	v_mul_f32_e32 v14, -2.0, v14
	v_mul_f32_e32 v14, 0x3fb8aa3b, v14
	v_exp_f32_e32 v14, v14
	v_and_b32_e32 v4, 0xffff0000, v4
	v_mul_f32_e32 v15, 0x3d372713, v4
	v_mul_f32_e32 v15, v15, v4
	v_add_f32_e32 v14, 1.0, v14
	v_rcp_f32_e32 v14, v14
	v_fma_f32 v15, v15, v4, v4
	v_mul_f32_e32 v15, 0x3f4c422a, v15
	v_mul_f32_e32 v15, -2.0, v15
	v_fma_f32 v13, v14, v13, -v8
	v_mov_b32_e32 v14, v124
	v_mov_b32_e32 v16, v156
	v_mul_f32_e32 v13, v9, v13
	v_mul_f32_e32 v15, 0x3fb8aa3b, v15
	v_exp_f32_e32 v15, v15
	v_fmac_f32_e32 v16, v13, v14
	v_cvt_pk_bf16_f32 v13, v16, v3
	ds_write_b16 v64, v13 offset:544
	v_mov_b32_e32 v13, v125
	v_mov_b32_e32 v14, v157
	v_add_f32_e32 v15, 1.0, v15
	v_rcp_f32_e32 v15, v15
	s_nop 0
	v_fma_f32 v4, v15, v4, -v8
	v_mul_f32_e32 v4, v9, v4
	v_fmac_f32_e32 v14, v4, v13
	v_cvt_pk_bf16_f32 v4, v14, v3
	ds_write_b16 v65, v4 offset:272
	v_lshlrev_b32_e32 v4, 16, v5
	v_mul_f32_e32 v13, 0x3d372713, v4
	v_mul_f32_e32 v13, v13, v4
	v_fma_f32 v13, v13, v4, v4
	v_mul_f32_e32 v13, 0x3f4c422a, v13
	v_mul_f32_e32 v13, -2.0, v13
	v_mul_f32_e32 v13, 0x3fb8aa3b, v13
	v_exp_f32_e32 v13, v13
	v_and_b32_e32 v5, 0xffff0000, v5
	v_mul_f32_e32 v14, 0x3d372713, v5
	v_mul_f32_e32 v14, v14, v5
	v_add_f32_e32 v13, 1.0, v13
	v_rcp_f32_e32 v13, v13
	v_fma_f32 v14, v14, v5, v5
	v_mul_f32_e32 v14, 0x3f4c422a, v14
	v_mul_f32_e32 v14, -2.0, v14
	v_fma_f32 v4, v13, v4, -v8
	v_mov_b32_e32 v13, v126
	v_mov_b32_e32 v15, v158
	v_mul_f32_e32 v14, 0x3fb8aa3b, v14
	v_exp_f32_e32 v14, v14
	v_mul_f32_e32 v4, v9, v4
	v_add_f32_e32 v14, 1.0, v14
	v_rcp_f32_e32 v14, v14
	v_fmac_f32_e32 v15, v4, v13
	v_cvt_pk_bf16_f32 v4, v15, v3
	ds_write_b16 v65, v4 offset:544
	v_fma_f32 v4, v14, v5, -v8
	v_mov_b32_e32 v5, v127
	v_mov_b32_e32 v13, v159
	v_mul_f32_e32 v4, v9, v4
	v_fmac_f32_e32 v13, v4, v5
	v_cvt_pk_bf16_f32 v4, v13, v3
	ds_write_b16 v66, v4 offset:272
	v_lshlrev_b32_e32 v4, 16, v6
	v_mul_f32_e32 v5, 0x3d372713, v4
	v_mul_f32_e32 v5, v5, v4
	v_fma_f32 v5, v5, v4, v4
	v_mul_f32_e32 v5, 0x3f4c422a, v5
	v_mul_f32_e32 v5, -2.0, v5
	v_mul_f32_e32 v5, 0x3fb8aa3b, v5
	v_exp_f32_e32 v5, v5
	v_and_b32_e32 v6, 0xffff0000, v6
	v_mul_f32_e32 v13, 0x3d372713, v6
	v_mul_f32_e32 v13, v13, v6
	v_add_f32_e32 v5, 1.0, v5
	v_rcp_f32_e32 v5, v5
	v_fma_f32 v13, v13, v6, v6
	v_mul_f32_e32 v13, 0x3f4c422a, v13
	v_mul_f32_e32 v13, -2.0, v13
	v_fma_f32 v4, v5, v4, -v8
	v_mov_b32_e32 v5, v128
	v_mov_b32_e32 v14, v160
	v_mul_f32_e32 v13, 0x3fb8aa3b, v13
	v_exp_f32_e32 v13, v13
	v_mul_f32_e32 v4, v9, v4
	v_add_f32_e32 v13, 1.0, v13
	v_rcp_f32_e32 v13, v13
	v_fmac_f32_e32 v14, v4, v5
	v_cvt_pk_bf16_f32 v4, v14, v3
	ds_write_b16 v66, v4 offset:544
	v_fma_f32 v4, v13, v6, -v8
	v_mov_b32_e32 v5, v129
	v_mov_b32_e32 v6, v161
	v_mul_f32_e32 v4, v9, v4
	v_fmac_f32_e32 v6, v4, v5
	v_cvt_pk_bf16_f32 v4, v6, v3
	ds_write_b16 v67, v4 offset:272
	v_lshlrev_b32_e32 v4, 16, v7
	v_mul_f32_e32 v5, 0x3d372713, v4
	v_mul_f32_e32 v5, v5, v4
	v_fma_f32 v5, v5, v4, v4
	v_mul_f32_e32 v5, 0x3f4c422a, v5
	v_mul_f32_e32 v5, -2.0, v5
	v_mul_f32_e32 v5, 0x3fb8aa3b, v5
	v_exp_f32_e32 v5, v5
	v_and_b32_e32 v6, 0xffff0000, v7
	v_mul_f32_e32 v7, 0x3d372713, v6
	v_mul_f32_e32 v7, v7, v6
	v_add_f32_e32 v5, 1.0, v5
	v_rcp_f32_e32 v5, v5
	v_fma_f32 v7, v7, v6, v6
	v_mul_f32_e32 v7, 0x3f4c422a, v7
	v_mul_f32_e32 v7, -2.0, v7
	v_fma_f32 v4, v5, v4, -v8
	v_mov_b32_e32 v5, v130
	v_mov_b32_e32 v13, v162
	v_mul_f32_e32 v7, 0x3fb8aa3b, v7
	v_exp_f32_e32 v7, v7
	v_mul_f32_e32 v4, v9, v4
	v_add_f32_e32 v7, 1.0, v7
	v_rcp_f32_e32 v7, v7
	v_fmac_f32_e32 v13, v4, v5
	v_cvt_pk_bf16_f32 v4, v13, v3
	ds_write_b16 v67, v4 offset:544
	v_fma_f32 v4, v7, v6, -v8
	v_mov_b32_e32 v5, v131
	v_mov_b32_e32 v6, v163
	v_mul_f32_e32 v4, v9, v4
	v_fmac_f32_e32 v6, v4, v5
	v_cvt_pk_bf16_f32 v4, v6, v3
	ds_write_b16 v68, v4 offset:272
	v_mov_b64_e32 v[4:5], v[104:105]
	v_mov_b64_e32 v[6:7], v[106:107]
	v_lshlrev_b32_e32 v13, 16, v4
	v_mul_f32_e32 v14, 0x3d372713, v13
	v_mul_f32_e32 v14, v14, v13
	v_fma_f32 v14, v14, v13, v13
	v_mul_f32_e32 v14, 0x3f4c422a, v14
	v_mul_f32_e32 v14, -2.0, v14
	v_mul_f32_e32 v14, 0x3fb8aa3b, v14
	v_exp_f32_e32 v14, v14
	v_and_b32_e32 v4, 0xffff0000, v4
	v_mul_f32_e32 v15, 0x3d372713, v4
; __device__ __forceinline__ float bf_lo(unsigned w) { return __uint_as_float(w << 16); }
; __device__ __forceinline__ float bf_hi(unsigned w) { return __uint_as_float(w & 0xffff0000u); }
; __device__ __forceinline__ bf16_t f2bf(float f) { return (bf16_t)(cvt_pk_bf16(f, 0.f) & 0xffffu); }
; __global__ void __launch_bounds__(NTHR, 2) mega_fwd(Args a) {
;     ...
;                     for (int i = 0; i < 4; ++i) { const u32x4 w = *(const u32x4*)(vp + 8 * i);
; #pragma unroll
;                         for (int j = 0; j < 4; ++j) { const int c = cq + 8 * i + 2 * j;
;                             const float x0 = gelu_tanh(bf_lo(w[j])), x1 = gelu_tanh(bf_hi(w[j]));
;                             vT[c * 136 + tok] = f2bf((x0 - mean) * rstd * lng[gi * 128 + c] + lnb[gi * 128 + c]);
;                             vT[(c + 1) * 136 + tok] = f2bf((x1 - mean) * rstd * lng[gi * 128 + c + 1] + lnb[gi * 128 + c + 1]); } }
	v_mul_f32_e32 v15, v15, v4
	v_add_f32_e32 v14, 1.0, v14
	v_rcp_f32_e32 v14, v14
	v_fma_f32 v15, v15, v4, v4
	v_mul_f32_e32 v15, 0x3f4c422a, v15
	v_mul_f32_e32 v15, -2.0, v15
	v_fma_f32 v13, v14, v13, -v8
	v_mov_b32_e32 v14, v132
	v_mov_b32_e32 v16, v164
	v_mul_f32_e32 v13, v9, v13
	v_mul_f32_e32 v15, 0x3fb8aa3b, v15
	v_exp_f32_e32 v15, v15
	v_fmac_f32_e32 v16, v13, v14
	v_cvt_pk_bf16_f32 v13, v16, v3
	ds_write_b16 v68, v13 offset:544
	v_mov_b32_e32 v13, v133
	v_mov_b32_e32 v14, v165
	v_add_f32_e32 v15, 1.0, v15
	v_rcp_f32_e32 v15, v15
	s_nop 0
	v_fma_f32 v4, v15, v4, -v8
	v_mul_f32_e32 v4, v9, v4
	v_fmac_f32_e32 v14, v4, v13
	v_cvt_pk_bf16_f32 v4, v14, v3
	ds_write_b16 v69, v4 offset:272
	v_lshlrev_b32_e32 v4, 16, v5
	v_mul_f32_e32 v13, 0x3d372713, v4
	v_mul_f32_e32 v13, v13, v4
	v_fma_f32 v13, v13, v4, v4
	v_mul_f32_e32 v13, 0x3f4c422a, v13
	v_mul_f32_e32 v13, -2.0, v13
	v_mul_f32_e32 v13, 0x3fb8aa3b, v13
	v_exp_f32_e32 v13, v13
	v_and_b32_e32 v5, 0xffff0000, v5
	v_mul_f32_e32 v14, 0x3d372713, v5
	v_mul_f32_e32 v14, v14, v5
	v_add_f32_e32 v13, 1.0, v13
	v_rcp_f32_e32 v13, v13
	v_fma_f32 v14, v14, v5, v5
	v_mul_f32_e32 v14, 0x3f4c422a, v14
	v_mul_f32_e32 v14, -2.0, v14
	v_fma_f32 v4, v13, v4, -v8
	v_mov_b32_e32 v13, v134
	v_mov_b32_e32 v15, v166
	v_mul_f32_e32 v14, 0x3fb8aa3b, v14
	v_exp_f32_e32 v14, v14
	v_mul_f32_e32 v4, v9, v4
	v_add_f32_e32 v14, 1.0, v14
	v_rcp_f32_e32 v14, v14
	v_fmac_f32_e32 v15, v4, v13
	v_cvt_pk_bf16_f32 v4, v15, v3
	ds_write_b16 v69, v4 offset:544
	v_fma_f32 v4, v14, v5, -v8
	v_mov_b32_e32 v5, v135
	v_mov_b32_e32 v13, v167
	v_mul_f32_e32 v4, v9, v4
	v_fmac_f32_e32 v13, v4, v5
	v_cvt_pk_bf16_f32 v4, v13, v3
	ds_write_b16 v70, v4 offset:272
	v_lshlrev_b32_e32 v4, 16, v6
	v_mul_f32_e32 v5, 0x3d372713, v4
	v_mul_f32_e32 v5, v5, v4
	v_fma_f32 v5, v5, v4, v4
	v_mul_f32_e32 v5, 0x3f4c422a, v5
	v_mul_f32_e32 v5, -2.0, v5
	v_mul_f32_e32 v5, 0x3fb8aa3b, v5
	v_exp_f32_e32 v5, v5
	v_and_b32_e32 v6, 0xffff0000, v6
	v_mul_f32_e32 v13, 0x3d372713, v6
	v_mul_f32_e32 v13, v13, v6
	v_add_f32_e32 v5, 1.0, v5
	v_rcp_f32_e32 v5, v5
	v_fma_f32 v13, v13, v6, v6
	v_mul_f32_e32 v13, 0x3f4c422a, v13
	v_mul_f32_e32 v13, -2.0, v13
	v_fma_f32 v4, v5, v4, -v8
	v_mov_b32_e32 v5, v136
	v_mov_b32_e32 v14, v168
	v_mul_f32_e32 v13, 0x3fb8aa3b, v13
	v_exp_f32_e32 v13, v13
	v_mul_f32_e32 v4, v9, v4
	v_add_f32_e32 v13, 1.0, v13
	v_rcp_f32_e32 v13, v13
	v_fmac_f32_e32 v14, v4, v5
	v_cvt_pk_bf16_f32 v4, v14, v3
	ds_write_b16 v70, v4 offset:544
	v_fma_f32 v4, v13, v6, -v8
	v_mov_b32_e32 v5, v137
	v_mov_b32_e32 v6, v169
	v_mul_f32_e32 v4, v9, v4
	v_fmac_f32_e32 v6, v4, v5
	v_cvt_pk_bf16_f32 v4, v6, v3
	ds_write_b16 v71, v4 offset:272
	v_lshlrev_b32_e32 v4, 16, v7
	v_mul_f32_e32 v5, 0x3d372713, v4
	v_mul_f32_e32 v5, v5, v4
	v_fma_f32 v5, v5, v4, v4
	v_mul_f32_e32 v5, 0x3f4c422a, v5
	v_mul_f32_e32 v5, -2.0, v5
	v_mul_f32_e32 v5, 0x3fb8aa3b, v5
	v_exp_f32_e32 v5, v5
	v_and_b32_e32 v6, 0xffff0000, v7
	v_mul_f32_e32 v7, 0x3d372713, v6
	v_mul_f32_e32 v7, v7, v6
	v_add_f32_e32 v5, 1.0, v5
	v_rcp_f32_e32 v5, v5
	v_fma_f32 v7, v7, v6, v6
	v_mul_f32_e32 v7, 0x3f4c422a, v7
	v_mul_f32_e32 v7, -2.0, v7
	v_fma_f32 v4, v5, v4, -v8
	v_mov_b32_e32 v5, v138
	v_mov_b32_e32 v13, v170
	v_mul_f32_e32 v7, 0x3fb8aa3b, v7
	v_exp_f32_e32 v7, v7
	v_mul_f32_e32 v4, v9, v4
	v_add_f32_e32 v7, 1.0, v7
	v_rcp_f32_e32 v7, v7
	v_fmac_f32_e32 v13, v4, v5
	v_cvt_pk_bf16_f32 v4, v13, v3
	ds_write_b16 v71, v4 offset:544
	v_fma_f32 v4, v7, v6, -v8
	v_mov_b32_e32 v5, v139
	v_mov_b32_e32 v6, v171
	v_mul_f32_e32 v4, v9, v4
	v_fmac_f32_e32 v6, v4, v5
	v_cvt_pk_bf16_f32 v4, v6, v3
	ds_write_b16 v72, v4 offset:272
	v_mov_b64_e32 v[4:5], v[108:109]
	v_mov_b64_e32 v[6:7], v[110:111]
	v_lshlrev_b32_e32 v10, 16, v4
	v_mul_f32_e32 v11, 0x3d372713, v10
	v_mul_f32_e32 v11, v11, v10
	v_fma_f32 v11, v11, v10, v10
	v_mul_f32_e32 v11, 0x3f4c422a, v11
	v_mul_f32_e32 v11, -2.0, v11
	v_mul_f32_e32 v11, 0x3fb8aa3b, v11
	v_exp_f32_e32 v11, v11
	v_and_b32_e32 v4, 0xffff0000, v4
	v_mul_f32_e32 v13, 0x3d372713, v4
	v_mul_f32_e32 v13, v13, v4
	v_add_f32_e32 v11, 1.0, v11
	v_rcp_f32_e32 v11, v11
	v_fma_f32 v13, v13, v4, v4
	v_mul_f32_e32 v13, 0x3f4c422a, v13
	v_mul_f32_e32 v13, -2.0, v13
	v_fma_f32 v10, v11, v10, -v8
	v_mov_b32_e32 v11, v140
	v_mov_b32_e32 v14, v172
	v_mul_f32_e32 v10, v9, v10
	v_mul_f32_e32 v13, 0x3fb8aa3b, v13
	v_exp_f32_e32 v13, v13
	v_fmac_f32_e32 v14, v10, v11
	v_cvt_pk_bf16_f32 v10, v14, v3
	ds_write_b16 v72, v10 offset:544
	v_mov_b32_e32 v10, v141
	v_mov_b32_e32 v11, v173
	v_add_f32_e32 v13, 1.0, v13
	v_rcp_f32_e32 v13, v13
	s_nop 0
	v_fma_f32 v4, v13, v4, -v8
	v_mul_f32_e32 v4, v9, v4
	v_fmac_f32_e32 v11, v4, v10
	v_cvt_pk_bf16_f32 v4, v11, v3
	ds_write_b16 v73, v4 offset:272
	v_lshlrev_b32_e32 v4, 16, v5
	v_mul_f32_e32 v10, 0x3d372713, v4
	v_mul_f32_e32 v10, v10, v4
	v_fma_f32 v10, v10, v4, v4
	v_mul_f32_e32 v10, 0x3f4c422a, v10
	v_mul_f32_e32 v10, -2.0, v10
	v_mul_f32_e32 v10, 0x3fb8aa3b, v10
	v_exp_f32_e32 v10, v10
	v_and_b32_e32 v5, 0xffff0000, v5
	v_mul_f32_e32 v11, 0x3d372713, v5
	v_mul_f32_e32 v11, v11, v5
	v_add_f32_e32 v10, 1.0, v10
	v_rcp_f32_e32 v10, v10
	v_fma_f32 v11, v11, v5, v5
	v_mul_f32_e32 v11, 0x3f4c422a, v11
	v_mul_f32_e32 v11, -2.0, v11
	v_fma_f32 v4, v10, v4, -v8
	v_mov_b32_e32 v10, v142
	v_mov_b32_e32 v13, v174
	v_mul_f32_e32 v11, 0x3fb8aa3b, v11
	v_exp_f32_e32 v11, v11
	v_mul_f32_e32 v4, v9, v4
	v_add_f32_e32 v11, 1.0, v11
	v_rcp_f32_e32 v11, v11
	v_fmac_f32_e32 v13, v4, v10
	v_cvt_pk_bf16_f32 v4, v13, v3
	ds_write_b16 v73, v4 offset:544
	v_fma_f32 v4, v11, v5, -v8
	v_mov_b32_e32 v5, v143
	v_mov_b32_e32 v10, v175
	v_mul_f32_e32 v4, v9, v4
	v_fmac_f32_e32 v10, v4, v5
; __device__ __forceinline__ float bf_lo(unsigned w) { return __uint_as_float(w << 16); }
; __device__ __forceinline__ float bf_hi(unsigned w) { return __uint_as_float(w & 0xffff0000u); }
; __device__ __forceinline__ bf16_t f2bf(float f) { return (bf16_t)(cvt_pk_bf16(f, 0.f) & 0xffffu); }
; __global__ void __launch_bounds__(NTHR, 2) mega_fwd(Args a) {
;     ...
;                     for (int i = 0; i < 4; ++i) { const u32x4 w = *(const u32x4*)(vp + 8 * i);
; #pragma unroll
;                         for (int j = 0; j < 4; ++j) { const int c = cq + 8 * i + 2 * j;
;                             const float x0 = gelu_tanh(bf_lo(w[j])), x1 = gelu_tanh(bf_hi(w[j]));
;                             vT[c * 136 + tok] = f2bf((x0 - mean) * rstd * lng[gi * 128 + c] + lnb[gi * 128 + c]);
;                             vT[(c + 1) * 136 + tok] = f2bf((x1 - mean) * rstd * lng[gi * 128 + c + 1] + lnb[gi * 128 + c + 1]); } }
;                 }
;                 __syncthreads();
;                 {
;                     f32x4 acc[8];
; #pragma unroll
;                     for (int ct = 0; ct < 8; ++ct) acc[ct] = (f32x4){0.f, 0.f, 0.f, 0.f};
;                     const bf16_t* wrow = wtril + ((size_t)(l * 4 + gi) * 128 + 16 * wave + (lane & 15)) * 128 + 8 * (lane >> 4);
; #pragma unroll
;                     for (int kk = 0; kk < 4; ++kk) { const bf16x8 av = *(const bf16x8*)(wrow + kk * 32);
; #pragma unroll
;                         for (int ct = 0; ct < 8; ++ct) { const bf16x8 bv = *(const bf16x8*)(vT + (ct * 16 + (lane & 15)) * 136 + kk * 32 + 8 * (lane >> 4));
;                             acc[ct] = __builtin_amdgcn_mfma_f32_16x16x32_bf16(av, bv, acc[ct], 0, 0, 0); } }
; #pragma unroll
	v_cvt_pk_bf16_f32 v4, v10, v3
	ds_write_b16 v74, v4 offset:272
	v_lshlrev_b32_e32 v4, 16, v6
	v_mul_f32_e32 v5, 0x3d372713, v4
	v_mul_f32_e32 v5, v5, v4
	v_fma_f32 v5, v5, v4, v4
	v_mul_f32_e32 v5, 0x3f4c422a, v5
	v_mul_f32_e32 v5, -2.0, v5
	v_mul_f32_e32 v5, 0x3fb8aa3b, v5
	v_exp_f32_e32 v5, v5
	v_and_b32_e32 v6, 0xffff0000, v6
	v_mul_f32_e32 v10, 0x3d372713, v6
	v_mul_f32_e32 v10, v10, v6
	v_add_f32_e32 v5, 1.0, v5
	v_rcp_f32_e32 v5, v5
	v_fma_f32 v10, v10, v6, v6
	v_mul_f32_e32 v10, 0x3f4c422a, v10
	v_mul_f32_e32 v10, -2.0, v10
	v_fma_f32 v4, v5, v4, -v8
	v_mov_b32_e32 v5, v144
	v_mov_b32_e32 v11, v176
	v_mul_f32_e32 v10, 0x3fb8aa3b, v10
	v_exp_f32_e32 v10, v10
	v_mul_f32_e32 v4, v9, v4
	v_add_f32_e32 v10, 1.0, v10
	v_rcp_f32_e32 v10, v10
	v_fmac_f32_e32 v11, v4, v5
	v_cvt_pk_bf16_f32 v4, v11, v3
	ds_write_b16 v74, v4 offset:544
	v_fma_f32 v4, v10, v6, -v8
	v_mov_b32_e32 v5, v145
	v_mov_b32_e32 v6, v177
	v_mul_f32_e32 v4, v9, v4
	v_fmac_f32_e32 v6, v4, v5
	v_cvt_pk_bf16_f32 v4, v6, v3
	ds_write_b16 v75, v4 offset:272
	v_lshlrev_b32_e32 v4, 16, v7
	v_mul_f32_e32 v5, 0x3d372713, v4
	v_mul_f32_e32 v5, v5, v4
	v_fma_f32 v5, v5, v4, v4
	v_mul_f32_e32 v5, 0x3f4c422a, v5
	v_mul_f32_e32 v5, -2.0, v5
	v_mul_f32_e32 v5, 0x3fb8aa3b, v5
	v_exp_f32_e32 v5, v5
	v_and_b32_e32 v6, 0xffff0000, v7
	v_mul_f32_e32 v7, 0x3d372713, v6
	v_mul_f32_e32 v7, v7, v6
	v_add_f32_e32 v5, 1.0, v5
	v_rcp_f32_e32 v5, v5
	v_fma_f32 v7, v7, v6, v6
	v_mul_f32_e32 v7, 0x3f4c422a, v7
	v_mul_f32_e32 v7, -2.0, v7
	v_fma_f32 v4, v5, v4, -v8
	v_mov_b32_e32 v5, v146
	v_mov_b32_e32 v10, v178
	v_mul_f32_e32 v7, 0x3fb8aa3b, v7
	v_exp_f32_e32 v7, v7
	v_mul_f32_e32 v4, v9, v4
	v_add_f32_e32 v7, 1.0, v7
	v_rcp_f32_e32 v7, v7
	v_fmac_f32_e32 v10, v4, v5
	v_cvt_pk_bf16_f32 v4, v10, v3
	ds_write_b16 v76, v4
	v_fma_f32 v4, v7, v6, -v8
	v_mov_b32_e32 v5, v147
	v_mov_b32_e32 v6, v179
	v_mul_f32_e32 v4, v9, v4
	v_fmac_f32_e32 v6, v4, v5
	v_cvt_pk_bf16_f32 v4, v6, v3
	ds_write_b16 v77, v4 offset:272
	v_lshl_add_u64 v[4:5], v[40:41], 0, s[30:31]
	v_lshlrev_b64 v[4:5], 8, v[4:5]
	v_lshl_add_u64 v[4:5], v[42:43], 0, v[4:5]
	s_waitcnt lgkmcnt(0)
	s_barrier
	s_waitcnt vmcnt(0)
	v_mov_b64_e32 v[6:7], v[180:181]
	v_mov_b64_e32 v[8:9], v[182:183]
	s_nop 1
	ds_read_b128 v[10:13], v79
	ds_read_b128 v[92:95], v79 offset:64
	ds_read_b128 v[14:17], v79 offset:4352
	ds_read_b128 v[18:21], v79 offset:8704
	ds_read_b128 v[22:25], v79 offset:13056
	ds_read_b128 v[26:29], v79 offset:17408
	ds_read_b128 v[30:33], v79 offset:21760
	ds_read_b128 v[84:87], v79 offset:26112
	ds_read_b128 v[88:91], v79 offset:30464
	s_waitcnt vmcnt(0) lgkmcnt(8)
	v_mfma_f32_16x16x32_bf16 v[10:13], v[6:9], v[10:13], 0
	s_lshl_b32 s30, s26, 8
	s_cmpk_gt_i32 s22, 0x1ff
	s_waitcnt lgkmcnt(6)
	v_mfma_f32_16x16x32_bf16 v[14:17], v[6:9], v[14:17], 0
	s_waitcnt lgkmcnt(5)
	v_mfma_f32_16x16x32_bf16 v[18:21], v[6:9], v[18:21], 0
	s_waitcnt lgkmcnt(4)
	v_mfma_f32_16x16x32_bf16 v[22:25], v[6:9], v[22:25], 0
	s_waitcnt lgkmcnt(3)
	v_mfma_f32_16x16x32_bf16 v[26:29], v[6:9], v[26:29], 0
	s_waitcnt lgkmcnt(2)
	v_mfma_f32_16x16x32_bf16 v[30:33], v[6:9], v[30:33], 0
	s_waitcnt lgkmcnt(1)
	v_mfma_f32_16x16x32_bf16 v[84:87], v[6:9], v[84:87], 0
	s_waitcnt lgkmcnt(0)
	v_mfma_f32_16x16x32_bf16 v[6:9], v[6:9], v[88:91], 0
	v_mov_b64_e32 v[88:89], v[184:185]
	v_mov_b64_e32 v[90:91], v[186:187]
	s_nop 1
	s_waitcnt vmcnt(0)
	v_mfma_f32_16x16x32_bf16 v[10:13], v[88:91], v[92:95], v[10:13]
	ds_read_b128 v[92:95], v79 offset:4416
	s_waitcnt lgkmcnt(0)
	v_mfma_f32_16x16x32_bf16 v[14:17], v[88:91], v[92:95], v[14:17]
	ds_read_b128 v[92:95], v79 offset:8768
	s_waitcnt lgkmcnt(0)
	v_mfma_f32_16x16x32_bf16 v[18:21], v[88:91], v[92:95], v[18:21]
	ds_read_b128 v[92:95], v79 offset:13120
	s_waitcnt lgkmcnt(0)
	v_mfma_f32_16x16x32_bf16 v[22:25], v[88:91], v[92:95], v[22:25]
	ds_read_b128 v[92:95], v79 offset:17472
	s_waitcnt lgkmcnt(0)
	v_mfma_f32_16x16x32_bf16 v[26:29], v[88:91], v[92:95], v[26:29]
	ds_read_b128 v[92:95], v79 offset:21824
	s_waitcnt lgkmcnt(0)
	v_mfma_f32_16x16x32_bf16 v[30:33], v[88:91], v[92:95], v[30:33]
	ds_read_b128 v[92:95], v79 offset:26176
	s_waitcnt lgkmcnt(0)
	v_mfma_f32_16x16x32_bf16 v[84:87], v[88:91], v[92:95], v[84:87]
	ds_read_b128 v[92:95], v79 offset:30528
	s_waitcnt lgkmcnt(0)
	v_mfma_f32_16x16x32_bf16 v[6:9], v[88:91], v[92:95], v[6:9]
	v_mov_b64_e32 v[88:89], v[188:189]
	v_mov_b64_e32 v[90:91], v[190:191]
	s_nop 1
	ds_read_b128 v[92:95], v79 offset:128
	s_waitcnt vmcnt(0) lgkmcnt(0)
	v_mfma_f32_16x16x32_bf16 v[10:13], v[88:91], v[92:95], v[10:13]
	ds_read_b128 v[92:95], v79 offset:4480
	s_waitcnt lgkmcnt(0)
	v_mfma_f32_16x16x32_bf16 v[14:17], v[88:91], v[92:95], v[14:17]
	ds_read_b128 v[92:95], v79 offset:8832
	s_waitcnt lgkmcnt(0)
	v_mfma_f32_16x16x32_bf16 v[18:21], v[88:91], v[92:95], v[18:21]
	ds_read_b128 v[92:95], v79 offset:13184
	s_waitcnt lgkmcnt(0)
	v_mfma_f32_16x16x32_bf16 v[22:25], v[88:91], v[92:95], v[22:25]
	ds_read_b128 v[92:95], v79 offset:17536
	s_waitcnt lgkmcnt(0)
	v_mfma_f32_16x16x32_bf16 v[26:29], v[88:91], v[92:95], v[26:29]
	ds_read_b128 v[92:95], v79 offset:21888
	s_waitcnt lgkmcnt(0)
	v_mfma_f32_16x16x32_bf16 v[30:33], v[88:91], v[92:95], v[30:33]
	ds_read_b128 v[92:95], v79 offset:26240
	s_waitcnt lgkmcnt(0)
	v_mfma_f32_16x16x32_bf16 v[84:87], v[88:91], v[92:95], v[84:87]
	ds_read_b128 v[92:95], v79 offset:30592
	s_waitcnt lgkmcnt(0)
	v_mfma_f32_16x16x32_bf16 v[88:91], v[88:91], v[92:95], v[6:9]
	v_mov_b64_e32 v[92:93], v[192:193]
	v_mov_b64_e32 v[94:95], v[194:195]
	s_nop 1
	s_nop 1
	ds_read_b128 v[4:7], v79 offset:192
	s_waitcnt vmcnt(0) lgkmcnt(0)
; __device__ __forceinline__ unsigned cvt_pk_bf16(float lo, float hi) { unsigned r; asm volatile("v_cvt_pk_bf16_f32 %0, %1, %2" : "=v"(r) : "v"(lo), "v"(hi)); return r; }
; __device__ __forceinline__ float bf_lo(unsigned w) { return __uint_as_float(w << 16); }
; __device__ __forceinline__ float bf_hi(unsigned w) { return __uint_as_float(w & 0xffff0000u); }
; __global__ void __launch_bounds__(NTHR, 2) mega_fwd(Args a) {
;     ...
;                     for (int kk = 0; kk < 4; ++kk) { const bf16x8 av = *(const bf16x8*)(wrow + kk * 32);
; #pragma unroll
;                         for (int ct = 0; ct < 8; ++ct) { const bf16x8 bv = *(const bf16x8*)(vT + (ct * 16 + (lane & 15)) * 136 + kk * 32 + 8 * (lane >> 4));
;                             acc[ct] = __builtin_amdgcn_mfma_f32_16x16x32_bf16(av, bv, acc[ct], 0, 0, 0); } }
; #pragma unroll
;                     for (int j = 0; j < 4; ++j) { const int t = 16 * wave + 4 * (lane >> 4) + j; const float bt = bs[gi * 128 + t];
; #pragma unroll
;                         for (int ct = 0; ct < 8; ++ct) svL[t * 132 + ct * 16 + (lane & 15)] = acc[ct][j] + bt; }
;                 }
;                 __syncthreads();
;                 {
;                     const int c0 = (tid & 15) * 8;
; #pragma unroll
;                     for (int i = 0; i < 4; ++i) { const int t = 32 * i + (tid >> 4);
;                         const u32x4 uw = *(const u32x4*)(PB + ((size_t)(12 + gi) * T + r0 + t) * 128 + c0);
;                         const f32x4 s0 = *(const f32x4*)(svL + t * 132 + c0), s1 = *(const f32x4*)(svL + t * 132 + c0 + 4);
;                         u32x4 w; w.x = cvt_pk_bf16(gelu_tanh(bf_lo(uw.x)) * s0[0], gelu_tanh(bf_hi(uw.x)) * s0[1]); w.y = cvt_pk_bf16(gelu_tanh(bf_lo(uw.y)) * s0[2], gelu_tanh(bf_hi(uw.y)) * s0[3]);
;                         w.z = cvt_pk_bf16(gelu_tanh(bf_lo(uw.z)) * s1[0], gelu_tanh(bf_hi(uw.z)) * s1[1]); w.w = cvt_pk_bf16(gelu_tanh(bf_lo(uw.w)) * s1[2], gelu_tanh(bf_hi(uw.w)) * s1[3]);
;                         *(u32x4*)(Y + (size_t)(r0 + t) * DM + 512 + gi * 128 + c0) = w; }
	v_mfma_f32_16x16x32_bf16 v[4:7], v[92:95], v[4:7], v[10:13]
	s_nop 2
	ds_read_b128 v[8:11], v79 offset:4544
	s_waitcnt lgkmcnt(0)
	v_mfma_f32_16x16x32_bf16 v[8:11], v[92:95], v[8:11], v[14:17]
	s_nop 2
	ds_read_b128 v[12:15], v79 offset:8896
	s_waitcnt lgkmcnt(0)
	v_mfma_f32_16x16x32_bf16 v[12:15], v[92:95], v[12:15], v[18:21]
	s_nop 2
	ds_read_b128 v[16:19], v79 offset:13248
	s_waitcnt lgkmcnt(0)
	v_mfma_f32_16x16x32_bf16 v[16:19], v[92:95], v[16:19], v[22:25]
	s_nop 2
	ds_read_b128 v[20:23], v79 offset:17600
	s_waitcnt lgkmcnt(0)
	v_mfma_f32_16x16x32_bf16 v[20:23], v[92:95], v[20:23], v[26:29]
	s_nop 2
	ds_read_b128 v[24:27], v79 offset:21952
	s_waitcnt lgkmcnt(0)
	v_mfma_f32_16x16x32_bf16 v[24:27], v[92:95], v[24:27], v[30:33]
	s_nop 2
	ds_read_b128 v[28:31], v79 offset:26304
	ds_read_b128 v[32:35], v79 offset:30656
	s_waitcnt lgkmcnt(1)
	v_mfma_f32_16x16x32_bf16 v[28:31], v[92:95], v[28:31], v[84:87]
	s_nop 2
	v_add_u32_e32 v84, s27, v58
	v_ashrrev_i32_e32 v85, 31, v84
	v_lshl_add_u64 v[84:85], v[84:85], 2, s[8:9]
	global_load_dwordx4 v[84:87], v[84:85], off
	s_waitcnt lgkmcnt(0)
	v_mfma_f32_16x16x32_bf16 v[32:35], v[92:95], v[32:35], v[88:91]
	s_waitcnt vmcnt(0)
	v_add_f32_e32 v4, v84, v4
	v_add_f32_e32 v8, v84, v8
	v_add_u32_e32 v88, 0xc000, v80
	ds_write2_b32 v88, v4, v8 offset1:16
	v_add_f32_e32 v4, v84, v12
	v_add_f32_e32 v8, v84, v16
	ds_write2_b32 v88, v4, v8 offset0:32 offset1:48
	v_add_f32_e32 v4, v84, v20
	v_add_f32_e32 v8, v84, v24
	ds_write2_b32 v88, v4, v8 offset0:64 offset1:80
	v_add_f32_e32 v4, v84, v28
	v_add_f32_e32 v8, v84, v32
	ds_write2_b32 v88, v4, v8 offset0:96 offset1:112
	v_add_f32_e32 v4, v85, v5
	v_add_f32_e32 v5, v85, v9
	ds_write2_b32 v88, v4, v5 offset0:132 offset1:148
	v_add_f32_e32 v4, v85, v13
	v_add_f32_e32 v5, v85, v17
	ds_write2_b32 v88, v4, v5 offset0:164 offset1:180
	v_add_f32_e32 v4, v85, v21
	v_add_f32_e32 v5, v85, v25
	ds_write2_b32 v88, v4, v5 offset0:196 offset1:212
	v_add_f32_e32 v4, v85, v29
	v_add_f32_e32 v5, v85, v33
	ds_write2_b32 v88, v4, v5 offset0:228 offset1:244
	v_add_f32_e32 v4, v86, v6
	v_add_f32_e32 v5, v86, v10
	v_add_u32_e32 v6, 0xc400, v80
	ds_write2_b32 v6, v4, v5 offset0:8 offset1:24
	v_add_f32_e32 v4, v86, v14
	v_add_f32_e32 v5, v86, v18
	ds_write2_b32 v6, v4, v5 offset0:40 offset1:56
	v_add_f32_e32 v4, v86, v22
	v_add_f32_e32 v5, v86, v26
	ds_write2_b32 v6, v4, v5 offset0:72 offset1:88
	v_add_f32_e32 v4, v86, v30
	v_add_f32_e32 v5, v86, v34
	ds_write2_b32 v6, v4, v5 offset0:104 offset1:120
	v_add_f32_e32 v4, v87, v7
	v_add_f32_e32 v5, v87, v11
	ds_write2_b32 v6, v4, v5 offset0:140 offset1:156
	v_add_f32_e32 v4, v87, v15
	v_add_f32_e32 v5, v87, v19
	ds_write2_b32 v6, v4, v5 offset0:172 offset1:188
	v_add_f32_e32 v4, v87, v23
	v_add_f32_e32 v5, v87, v27
	ds_write2_b32 v6, v4, v5 offset0:204 offset1:220
	v_add_f32_e32 v4, v87, v31
	v_add_f32_e32 v5, v87, v35
	ds_write2_b32 v6, v4, v5 offset0:236 offset1:252
	v_lshl_add_u64 v[4:5], s[14:15], 0, v[44:45]
	v_lshlrev_b64 v[4:5], 8, v[4:5]
	v_lshl_add_u64 v[4:5], v[46:47], 0, v[4:5]
	s_waitcnt lgkmcnt(0)
	s_barrier
	v_mov_b64_e32 v[4:5], v[218:219]
	v_mov_b64_e32 v[6:7], v[220:221]
	v_add_u32_e32 v12, v59, v78
	ds_read_b128 v[8:11], v12 offset:49152
	ds_read_b128 v[12:15], v12 offset:49168
	s_waitcnt vmcnt(0)
	v_lshlrev_b32_e32 v16, 16, v4
	v_mul_f32_e32 v17, 0x3d372713, v16
	v_mul_f32_e32 v17, v17, v16
	v_fma_f32 v17, v17, v16, v16
	v_mul_f32_e32 v17, 0x3f4c422a, v17
	v_mul_f32_e32 v17, -2.0, v17
	v_mul_f32_e32 v17, 0x3fb8aa3b, v17
	v_exp_f32_e32 v17, v17
	v_and_b32_e32 v4, 0xffff0000, v4
	v_add_f32_e32 v17, 1.0, v17
	v_rcp_f32_e32 v17, v17
	s_nop 0
	v_mul_f32_e32 v16, v17, v16
	s_waitcnt lgkmcnt(1)
	v_mul_f32_e32 v8, v8, v16
	v_mul_f32_e32 v16, 0x3d372713, v4
	v_mul_f32_e32 v16, v16, v4
	v_fma_f32 v16, v16, v4, v4
	v_mul_f32_e32 v16, 0x3f4c422a, v16
	v_mul_f32_e32 v16, -2.0, v16
	v_mul_f32_e32 v16, 0x3fb8aa3b, v16
	v_exp_f32_e32 v16, v16
	s_nop 0
	v_add_f32_e32 v16, 1.0, v16
	v_rcp_f32_e32 v16, v16
	s_nop 0
	v_mul_f32_e32 v4, v16, v4
	v_mul_f32_e32 v4, v9, v4
	v_cvt_pk_bf16_f32 v4, v8, v4
	v_lshlrev_b32_e32 v8, 16, v5
	v_mul_f32_e32 v9, 0x3d372713, v8
	v_mul_f32_e32 v9, v9, v8
	v_fma_f32 v9, v9, v8, v8
	v_mul_f32_e32 v9, 0x3f4c422a, v9
	v_mul_f32_e32 v9, -2.0, v9
	v_mul_f32_e32 v9, 0x3fb8aa3b, v9
	v_exp_f32_e32 v9, v9
	v_and_b32_e32 v5, 0xffff0000, v5
	v_add_f32_e32 v9, 1.0, v9
	v_rcp_f32_e32 v9, v9
	s_nop 0
	v_mul_f32_e32 v8, v9, v8
	v_mul_f32_e32 v9, 0x3d372713, v5
	v_mul_f32_e32 v9, v9, v5
	v_fma_f32 v9, v9, v5, v5
	v_mul_f32_e32 v9, 0x3f4c422a, v9
	v_mul_f32_e32 v9, -2.0, v9
	v_mul_f32_e32 v9, 0x3fb8aa3b, v9
	v_exp_f32_e32 v9, v9
	v_mul_f32_e32 v8, v10, v8
	v_add_f32_e32 v9, 1.0, v9
	v_rcp_f32_e32 v9, v9
	s_nop 0
	v_mul_f32_e32 v5, v9, v5
	v_mul_f32_e32 v5, v11, v5
	v_cvt_pk_bf16_f32 v5, v8, v5
	v_lshlrev_b32_e32 v8, 16, v6
	v_mul_f32_e32 v9, 0x3d372713, v8
	v_mul_f32_e32 v9, v9, v8
	v_fma_f32 v9, v9, v8, v8
	v_mul_f32_e32 v9, 0x3f4c422a, v9
	v_mul_f32_e32 v9, -2.0, v9
	v_mul_f32_e32 v9, 0x3fb8aa3b, v9
	v_exp_f32_e32 v9, v9
	v_and_b32_e32 v6, 0xffff0000, v6
	v_add_f32_e32 v9, 1.0, v9
	v_rcp_f32_e32 v9, v9
	s_nop 0
	v_mul_f32_e32 v8, v9, v8
	v_mul_f32_e32 v9, 0x3d372713, v6
	v_mul_f32_e32 v9, v9, v6
	v_fma_f32 v9, v9, v6, v6
	v_mul_f32_e32 v9, 0x3f4c422a, v9
	v_mul_f32_e32 v9, -2.0, v9
	v_mul_f32_e32 v9, 0x3fb8aa3b, v9
	v_exp_f32_e32 v9, v9
	s_waitcnt lgkmcnt(0)
; __device__ __forceinline__ unsigned cvt_pk_bf16(float lo, float hi) { unsigned r; asm volatile("v_cvt_pk_bf16_f32 %0, %1, %2" : "=v"(r) : "v"(lo), "v"(hi)); return r; }
; __device__ __forceinline__ float bf_lo(unsigned w) { return __uint_as_float(w << 16); }
; __device__ __forceinline__ float bf_hi(unsigned w) { return __uint_as_float(w & 0xffff0000u); }
; __global__ void __launch_bounds__(NTHR, 2) mega_fwd(Args a) {
;     ...
;                 {
;                     const int c0 = (tid & 15) * 8;
; #pragma unroll
;                     for (int i = 0; i < 4; ++i) { const int t = 32 * i + (tid >> 4);
;                         const u32x4 uw = *(const u32x4*)(PB + ((size_t)(12 + gi) * T + r0 + t) * 128 + c0);
;                         const f32x4 s0 = *(const f32x4*)(svL + t * 132 + c0), s1 = *(const f32x4*)(svL + t * 132 + c0 + 4);
;                         u32x4 w; w.x = cvt_pk_bf16(gelu_tanh(bf_lo(uw.x)) * s0[0], gelu_tanh(bf_hi(uw.x)) * s0[1]); w.y = cvt_pk_bf16(gelu_tanh(bf_lo(uw.y)) * s0[2], gelu_tanh(bf_hi(uw.y)) * s0[3]);
;                         w.z = cvt_pk_bf16(gelu_tanh(bf_lo(uw.z)) * s1[0], gelu_tanh(bf_hi(uw.z)) * s1[1]); w.w = cvt_pk_bf16(gelu_tanh(bf_lo(uw.w)) * s1[2], gelu_tanh(bf_hi(uw.w)) * s1[3]);
;                         *(u32x4*)(Y + (size_t)(r0 + t) * DM + 512 + gi * 128 + c0) = w; }
	v_mul_f32_e32 v8, v12, v8
	v_add_f32_e32 v9, 1.0, v9
	v_rcp_f32_e32 v9, v9
	s_nop 0
	v_mul_f32_e32 v6, v9, v6
	v_mul_f32_e32 v6, v13, v6
	v_cvt_pk_bf16_f32 v6, v8, v6
	v_lshlrev_b32_e32 v8, 16, v7
	v_mul_f32_e32 v9, 0x3d372713, v8
	v_mul_f32_e32 v9, v9, v8
	v_fma_f32 v9, v9, v8, v8
	v_mul_f32_e32 v9, 0x3f4c422a, v9
	v_mul_f32_e32 v9, -2.0, v9
	v_mul_f32_e32 v9, 0x3fb8aa3b, v9
	v_exp_f32_e32 v9, v9
	v_and_b32_e32 v7, 0xffff0000, v7
	v_add_f32_e32 v9, 1.0, v9
	v_rcp_f32_e32 v9, v9
	s_nop 0
	v_mul_f32_e32 v8, v9, v8
	v_mul_f32_e32 v9, 0x3d372713, v7
	v_mul_f32_e32 v9, v9, v7
	v_fma_f32 v9, v9, v7, v7
	v_mul_f32_e32 v9, 0x3f4c422a, v9
	v_mul_f32_e32 v9, -2.0, v9
	v_mul_f32_e32 v9, 0x3fb8aa3b, v9
	v_exp_f32_e32 v9, v9
	v_mul_f32_e32 v8, v14, v8
	v_add_f32_e32 v9, 1.0, v9
	v_rcp_f32_e32 v9, v9
	s_nop 0
	v_mul_f32_e32 v7, v9, v7
	v_mul_f32_e32 v7, v15, v7
	v_cvt_pk_bf16_f32 v7, v8, v7
	v_add_u32_e32 v8, s23, v44
	v_ashrrev_i32_e32 v9, 31, v8
	v_lshlrev_b64 v[8:9], 12, v[8:9]
	v_lshl_add_u64 v[8:9], s[0:1], 0, v[8:9]
	v_lshl_add_u64 v[8:9], v[8:9], 0, s[30:31]
	v_lshl_add_u64 v[8:9], v[8:9], 0, v[2:3]
	v_add_co_u32_e32 v8, vcc, s49, v8
	s_nop 1
	v_addc_co_u32_e32 v9, vcc, 0, v9, vcc
	global_store_dwordx4 v[8:9], v[4:7], off offset:1024
	s_nop 1
	v_lshl_add_u64 v[4:5], s[14:15], 0, v[48:49]
	v_lshlrev_b64 v[4:5], 8, v[4:5]
	v_lshl_add_u64 v[4:5], v[46:47], 0, v[4:5]
	v_mov_b64_e32 v[4:5], v[222:223]
	v_mov_b64_e32 v[6:7], v[224:225]
	ds_read_b128 v[8:11], v81 offset:49152
	ds_read_b128 v[12:15], v81 offset:49168
	v_lshlrev_b32_e32 v16, 16, v4
	v_mul_f32_e32 v17, 0x3d372713, v16
	v_mul_f32_e32 v17, v17, v16
	v_fma_f32 v17, v17, v16, v16
	v_mul_f32_e32 v17, 0x3f4c422a, v17
	v_mul_f32_e32 v17, -2.0, v17
	v_mul_f32_e32 v17, 0x3fb8aa3b, v17
	v_exp_f32_e32 v17, v17
	v_and_b32_e32 v4, 0xffff0000, v4
	v_add_f32_e32 v17, 1.0, v17
	v_rcp_f32_e32 v17, v17
	s_nop 0
	v_mul_f32_e32 v16, v17, v16
	s_waitcnt lgkmcnt(1)
	v_mul_f32_e32 v8, v8, v16
	v_mul_f32_e32 v16, 0x3d372713, v4
	v_mul_f32_e32 v16, v16, v4
	v_fma_f32 v16, v16, v4, v4
	v_mul_f32_e32 v16, 0x3f4c422a, v16
	v_mul_f32_e32 v16, -2.0, v16
	v_mul_f32_e32 v16, 0x3fb8aa3b, v16
	v_exp_f32_e32 v16, v16
	s_nop 0
	v_add_f32_e32 v16, 1.0, v16
	v_rcp_f32_e32 v16, v16
	s_nop 0
	v_mul_f32_e32 v4, v16, v4
	v_mul_f32_e32 v4, v9, v4
	v_cvt_pk_bf16_f32 v4, v8, v4
	v_lshlrev_b32_e32 v8, 16, v5
	v_mul_f32_e32 v9, 0x3d372713, v8
	v_mul_f32_e32 v9, v9, v8
	v_fma_f32 v9, v9, v8, v8
	v_mul_f32_e32 v9, 0x3f4c422a, v9
	v_mul_f32_e32 v9, -2.0, v9
	v_mul_f32_e32 v9, 0x3fb8aa3b, v9
	v_exp_f32_e32 v9, v9
	v_and_b32_e32 v5, 0xffff0000, v5
	v_add_f32_e32 v9, 1.0, v9
	v_rcp_f32_e32 v9, v9
	s_nop 0
	v_mul_f32_e32 v8, v9, v8
	v_mul_f32_e32 v9, 0x3d372713, v5
	v_mul_f32_e32 v9, v9, v5
	v_fma_f32 v9, v9, v5, v5
	v_mul_f32_e32 v9, 0x3f4c422a, v9
	v_mul_f32_e32 v9, -2.0, v9
	v_mul_f32_e32 v9, 0x3fb8aa3b, v9
	v_exp_f32_e32 v9, v9
	v_mul_f32_e32 v8, v10, v8
	v_add_f32_e32 v9, 1.0, v9
	v_rcp_f32_e32 v9, v9
	s_nop 0
	v_mul_f32_e32 v5, v9, v5
	v_mul_f32_e32 v5, v11, v5
	v_cvt_pk_bf16_f32 v5, v8, v5
	v_lshlrev_b32_e32 v8, 16, v6
	v_mul_f32_e32 v9, 0x3d372713, v8
	v_mul_f32_e32 v9, v9, v8
	v_fma_f32 v9, v9, v8, v8
	v_mul_f32_e32 v9, 0x3f4c422a, v9
	v_mul_f32_e32 v9, -2.0, v9
	v_mul_f32_e32 v9, 0x3fb8aa3b, v9
	v_exp_f32_e32 v9, v9
	v_and_b32_e32 v6, 0xffff0000, v6
	v_add_f32_e32 v9, 1.0, v9
	v_rcp_f32_e32 v9, v9
	s_nop 0
	v_mul_f32_e32 v8, v9, v8
	v_mul_f32_e32 v9, 0x3d372713, v6
	v_mul_f32_e32 v9, v9, v6
	v_fma_f32 v9, v9, v6, v6
	v_mul_f32_e32 v9, 0x3f4c422a, v9
	v_mul_f32_e32 v9, -2.0, v9
	v_mul_f32_e32 v9, 0x3fb8aa3b, v9
	v_exp_f32_e32 v9, v9
	s_waitcnt lgkmcnt(0)
	v_mul_f32_e32 v8, v12, v8
	v_add_f32_e32 v9, 1.0, v9
	v_rcp_f32_e32 v9, v9
	s_nop 0
	v_mul_f32_e32 v6, v9, v6
	v_mul_f32_e32 v6, v13, v6
	v_cvt_pk_bf16_f32 v6, v8, v6
	v_lshlrev_b32_e32 v8, 16, v7
	v_mul_f32_e32 v9, 0x3d372713, v8
	v_mul_f32_e32 v9, v9, v8
	v_fma_f32 v9, v9, v8, v8
	v_mul_f32_e32 v9, 0x3f4c422a, v9
	v_mul_f32_e32 v9, -2.0, v9
	v_mul_f32_e32 v9, 0x3fb8aa3b, v9
	v_exp_f32_e32 v9, v9
	v_and_b32_e32 v7, 0xffff0000, v7
	v_add_f32_e32 v9, 1.0, v9
	v_rcp_f32_e32 v9, v9
	s_nop 0
	v_mul_f32_e32 v8, v9, v8
	v_mul_f32_e32 v9, 0x3d372713, v7
	v_mul_f32_e32 v9, v9, v7
	v_fma_f32 v9, v9, v7, v7
	v_mul_f32_e32 v9, 0x3f4c422a, v9
	v_mul_f32_e32 v9, -2.0, v9
	v_mul_f32_e32 v9, 0x3fb8aa3b, v9
	v_exp_f32_e32 v9, v9
	v_mul_f32_e32 v8, v14, v8
	v_add_f32_e32 v9, 1.0, v9
	v_rcp_f32_e32 v9, v9
	s_nop 0
	v_mul_f32_e32 v7, v9, v7
	v_mul_f32_e32 v7, v15, v7
	v_cvt_pk_bf16_f32 v7, v8, v7
	v_add_u32_e32 v8, s23, v48
	v_ashrrev_i32_e32 v9, 31, v8
	v_lshlrev_b64 v[8:9], 12, v[8:9]
	v_lshl_add_u64 v[8:9], s[0:1], 0, v[8:9]
	v_lshl_add_u64 v[8:9], v[8:9], 0, s[30:31]
	v_lshl_add_u64 v[8:9], v[8:9], 0, v[2:3]
	v_add_co_u32_e32 v8, vcc, s49, v8
	s_nop 1
	v_addc_co_u32_e32 v9, vcc, 0, v9, vcc
	global_store_dwordx4 v[8:9], v[4:7], off offset:1024
	s_nop 1
	v_lshl_add_u64 v[4:5], s[14:15], 0, v[50:51]
	v_lshlrev_b64 v[4:5], 8, v[4:5]
	v_lshl_add_u64 v[4:5], v[46:47], 0, v[4:5]
	v_mov_b64_e32 v[4:5], v[226:227]
	v_mov_b64_e32 v[6:7], v[228:229]
	ds_read_b128 v[8:11], v82 offset:49152
	ds_read_b128 v[12:15], v82 offset:49168
	v_lshlrev_b32_e32 v16, 16, v4
	v_mul_f32_e32 v17, 0x3d372713, v16
	v_mul_f32_e32 v17, v17, v16
	v_fma_f32 v17, v17, v16, v16
	v_mul_f32_e32 v17, 0x3f4c422a, v17
	v_mul_f32_e32 v17, -2.0, v17
	v_mul_f32_e32 v17, 0x3fb8aa3b, v17
	v_exp_f32_e32 v17, v17
	v_and_b32_e32 v4, 0xffff0000, v4
	v_add_f32_e32 v17, 1.0, v17
	v_rcp_f32_e32 v17, v17
	s_nop 0
	v_mul_f32_e32 v16, v17, v16
	s_waitcnt lgkmcnt(1)
; __device__ __forceinline__ unsigned cvt_pk_bf16(float lo, float hi) { unsigned r; asm volatile("v_cvt_pk_bf16_f32 %0, %1, %2" : "=v"(r) : "v"(lo), "v"(hi)); return r; }
; __device__ __forceinline__ float bf_lo(unsigned w) { return __uint_as_float(w << 16); }
; __device__ __forceinline__ float bf_hi(unsigned w) { return __uint_as_float(w & 0xffff0000u); }
; __global__ void __launch_bounds__(NTHR, 2) mega_fwd(Args a) {
;     ...
;                 {
;                     const int c0 = (tid & 15) * 8;
; #pragma unroll
;                     for (int i = 0; i < 4; ++i) { const int t = 32 * i + (tid >> 4);
;                         const u32x4 uw = *(const u32x4*)(PB + ((size_t)(12 + gi) * T + r0 + t) * 128 + c0);
;                         const f32x4 s0 = *(const f32x4*)(svL + t * 132 + c0), s1 = *(const f32x4*)(svL + t * 132 + c0 + 4);
;                         u32x4 w; w.x = cvt_pk_bf16(gelu_tanh(bf_lo(uw.x)) * s0[0], gelu_tanh(bf_hi(uw.x)) * s0[1]); w.y = cvt_pk_bf16(gelu_tanh(bf_lo(uw.y)) * s0[2], gelu_tanh(bf_hi(uw.y)) * s0[3]);
;                         w.z = cvt_pk_bf16(gelu_tanh(bf_lo(uw.z)) * s1[0], gelu_tanh(bf_hi(uw.z)) * s1[1]); w.w = cvt_pk_bf16(gelu_tanh(bf_lo(uw.w)) * s1[2], gelu_tanh(bf_hi(uw.w)) * s1[3]);
;                         *(u32x4*)(Y + (size_t)(r0 + t) * DM + 512 + gi * 128 + c0) = w; }
;                 }
;                 __syncthreads();
	v_mul_f32_e32 v8, v8, v16
	v_mul_f32_e32 v16, 0x3d372713, v4
	v_mul_f32_e32 v16, v16, v4
	v_fma_f32 v16, v16, v4, v4
	v_mul_f32_e32 v16, 0x3f4c422a, v16
	v_mul_f32_e32 v16, -2.0, v16
	v_mul_f32_e32 v16, 0x3fb8aa3b, v16
	v_exp_f32_e32 v16, v16
	s_nop 0
	v_add_f32_e32 v16, 1.0, v16
	v_rcp_f32_e32 v16, v16
	s_nop 0
	v_mul_f32_e32 v4, v16, v4
	v_mul_f32_e32 v4, v9, v4
	v_cvt_pk_bf16_f32 v4, v8, v4
	v_lshlrev_b32_e32 v8, 16, v5
	v_mul_f32_e32 v9, 0x3d372713, v8
	v_mul_f32_e32 v9, v9, v8
	v_fma_f32 v9, v9, v8, v8
	v_mul_f32_e32 v9, 0x3f4c422a, v9
	v_mul_f32_e32 v9, -2.0, v9
	v_mul_f32_e32 v9, 0x3fb8aa3b, v9
	v_exp_f32_e32 v9, v9
	v_and_b32_e32 v5, 0xffff0000, v5
	v_add_f32_e32 v9, 1.0, v9
	v_rcp_f32_e32 v9, v9
	s_nop 0
	v_mul_f32_e32 v8, v9, v8
	v_mul_f32_e32 v9, 0x3d372713, v5
	v_mul_f32_e32 v9, v9, v5
	v_fma_f32 v9, v9, v5, v5
	v_mul_f32_e32 v9, 0x3f4c422a, v9
	v_mul_f32_e32 v9, -2.0, v9
	v_mul_f32_e32 v9, 0x3fb8aa3b, v9
	v_exp_f32_e32 v9, v9
	v_mul_f32_e32 v8, v10, v8
	v_add_f32_e32 v9, 1.0, v9
	v_rcp_f32_e32 v9, v9
	s_nop 0
	v_mul_f32_e32 v5, v9, v5
	v_mul_f32_e32 v5, v11, v5
	v_cvt_pk_bf16_f32 v5, v8, v5
	v_lshlrev_b32_e32 v8, 16, v6
	v_mul_f32_e32 v9, 0x3d372713, v8
	v_mul_f32_e32 v9, v9, v8
	v_fma_f32 v9, v9, v8, v8
	v_mul_f32_e32 v9, 0x3f4c422a, v9
	v_mul_f32_e32 v9, -2.0, v9
	v_mul_f32_e32 v9, 0x3fb8aa3b, v9
	v_exp_f32_e32 v9, v9
	v_and_b32_e32 v6, 0xffff0000, v6
	v_add_f32_e32 v9, 1.0, v9
	v_rcp_f32_e32 v9, v9
	s_nop 0
	v_mul_f32_e32 v8, v9, v8
	v_mul_f32_e32 v9, 0x3d372713, v6
	v_mul_f32_e32 v9, v9, v6
	v_fma_f32 v9, v9, v6, v6
	v_mul_f32_e32 v9, 0x3f4c422a, v9
	v_mul_f32_e32 v9, -2.0, v9
	v_mul_f32_e32 v9, 0x3fb8aa3b, v9
	v_exp_f32_e32 v9, v9
	s_waitcnt lgkmcnt(0)
	v_mul_f32_e32 v8, v12, v8
	v_add_f32_e32 v9, 1.0, v9
	v_rcp_f32_e32 v9, v9
	s_nop 0
	v_mul_f32_e32 v6, v9, v6
	v_mul_f32_e32 v6, v13, v6
	v_cvt_pk_bf16_f32 v6, v8, v6
	v_lshlrev_b32_e32 v8, 16, v7
	v_mul_f32_e32 v9, 0x3d372713, v8
	v_mul_f32_e32 v9, v9, v8
	v_fma_f32 v9, v9, v8, v8
	v_mul_f32_e32 v9, 0x3f4c422a, v9
	v_mul_f32_e32 v9, -2.0, v9
	v_mul_f32_e32 v9, 0x3fb8aa3b, v9
	v_exp_f32_e32 v9, v9
	v_and_b32_e32 v7, 0xffff0000, v7
	v_add_f32_e32 v9, 1.0, v9
	v_rcp_f32_e32 v9, v9
	s_nop 0
	v_mul_f32_e32 v8, v9, v8
	v_mul_f32_e32 v9, 0x3d372713, v7
	v_mul_f32_e32 v9, v9, v7
	v_fma_f32 v9, v9, v7, v7
	v_mul_f32_e32 v9, 0x3f4c422a, v9
	v_mul_f32_e32 v9, -2.0, v9
	v_mul_f32_e32 v9, 0x3fb8aa3b, v9
	v_exp_f32_e32 v9, v9
	v_mul_f32_e32 v8, v14, v8
	v_add_f32_e32 v9, 1.0, v9
	v_rcp_f32_e32 v9, v9
	s_nop 0
	v_mul_f32_e32 v7, v9, v7
	v_mul_f32_e32 v7, v15, v7
	v_cvt_pk_bf16_f32 v7, v8, v7
	v_add_u32_e32 v8, s23, v50
	v_ashrrev_i32_e32 v9, 31, v8
	v_lshlrev_b64 v[8:9], 12, v[8:9]
	v_lshl_add_u64 v[8:9], s[0:1], 0, v[8:9]
	v_lshl_add_u64 v[8:9], v[8:9], 0, s[30:31]
	v_lshl_add_u64 v[8:9], v[8:9], 0, v[2:3]
	v_add_co_u32_e32 v8, vcc, s49, v8
	s_nop 1
	v_addc_co_u32_e32 v9, vcc, 0, v9, vcc
	global_store_dwordx4 v[8:9], v[4:7], off offset:1024
	s_nop 1
	v_lshl_add_u64 v[4:5], s[14:15], 0, v[52:53]
	v_lshlrev_b64 v[4:5], 8, v[4:5]
	v_lshl_add_u64 v[4:5], v[46:47], 0, v[4:5]
	v_mov_b64_e32 v[4:5], v[230:231]
	v_mov_b64_e32 v[6:7], v[232:233]
	ds_read_b128 v[8:11], v83 offset:49152
	ds_read_b128 v[12:15], v83 offset:49168
	v_lshlrev_b32_e32 v16, 16, v4
	v_mul_f32_e32 v17, 0x3d372713, v16
	v_mul_f32_e32 v17, v17, v16
	v_fma_f32 v17, v17, v16, v16
	v_mul_f32_e32 v17, 0x3f4c422a, v17
	v_mul_f32_e32 v17, -2.0, v17
	v_mul_f32_e32 v17, 0x3fb8aa3b, v17
	v_exp_f32_e32 v17, v17
	v_and_b32_e32 v4, 0xffff0000, v4
	v_add_f32_e32 v17, 1.0, v17
	v_rcp_f32_e32 v17, v17
	s_nop 0
	v_mul_f32_e32 v16, v17, v16
	s_waitcnt lgkmcnt(1)
	v_mul_f32_e32 v8, v8, v16
	v_mul_f32_e32 v16, 0x3d372713, v4
	v_mul_f32_e32 v16, v16, v4
	v_fma_f32 v16, v16, v4, v4
	v_mul_f32_e32 v16, 0x3f4c422a, v16
	v_mul_f32_e32 v16, -2.0, v16
	v_mul_f32_e32 v16, 0x3fb8aa3b, v16
	v_exp_f32_e32 v16, v16
	s_nop 0
	v_add_f32_e32 v16, 1.0, v16
	v_rcp_f32_e32 v16, v16
	s_nop 0
	v_mul_f32_e32 v4, v16, v4
	v_mul_f32_e32 v4, v9, v4
	v_cvt_pk_bf16_f32 v4, v8, v4
	v_lshlrev_b32_e32 v8, 16, v5
	v_mul_f32_e32 v9, 0x3d372713, v8
	v_mul_f32_e32 v9, v9, v8
	v_fma_f32 v9, v9, v8, v8
	v_mul_f32_e32 v9, 0x3f4c422a, v9
	v_mul_f32_e32 v9, -2.0, v9
	v_mul_f32_e32 v9, 0x3fb8aa3b, v9
	v_exp_f32_e32 v9, v9
	v_and_b32_e32 v5, 0xffff0000, v5
	v_add_f32_e32 v9, 1.0, v9
	v_rcp_f32_e32 v9, v9
	s_nop 0
	v_mul_f32_e32 v8, v9, v8
	v_mul_f32_e32 v9, 0x3d372713, v5
	v_mul_f32_e32 v9, v9, v5
	v_fma_f32 v9, v9, v5, v5
	v_mul_f32_e32 v9, 0x3f4c422a, v9
	v_mul_f32_e32 v9, -2.0, v9
	v_mul_f32_e32 v9, 0x3fb8aa3b, v9
	v_exp_f32_e32 v9, v9
	v_mul_f32_e32 v8, v10, v8
	v_add_f32_e32 v9, 1.0, v9
	v_rcp_f32_e32 v9, v9
	s_nop 0
	v_mul_f32_e32 v5, v9, v5
	v_mul_f32_e32 v5, v11, v5
	v_cvt_pk_bf16_f32 v5, v8, v5
	v_lshlrev_b32_e32 v8, 16, v6
	v_mul_f32_e32 v9, 0x3d372713, v8
	v_mul_f32_e32 v9, v9, v8
	v_fma_f32 v9, v9, v8, v8
	v_mul_f32_e32 v9, 0x3f4c422a, v9
	v_mul_f32_e32 v9, -2.0, v9
	v_mul_f32_e32 v9, 0x3fb8aa3b, v9
	v_exp_f32_e32 v9, v9
	v_and_b32_e32 v6, 0xffff0000, v6
	v_add_f32_e32 v9, 1.0, v9
	v_rcp_f32_e32 v9, v9
	s_nop 0
	v_mul_f32_e32 v8, v9, v8
	v_mul_f32_e32 v9, 0x3d372713, v6
	v_mul_f32_e32 v9, v9, v6
	v_fma_f32 v9, v9, v6, v6
	v_mul_f32_e32 v9, 0x3f4c422a, v9
	v_mul_f32_e32 v9, -2.0, v9
	v_mul_f32_e32 v9, 0x3fb8aa3b, v9
	v_exp_f32_e32 v9, v9
	s_waitcnt lgkmcnt(0)
	v_mul_f32_e32 v8, v12, v8
	v_add_f32_e32 v9, 1.0, v9
	v_rcp_f32_e32 v9, v9
	s_nop 0
	v_mul_f32_e32 v6, v9, v6
	v_mul_f32_e32 v6, v13, v6
	v_cvt_pk_bf16_f32 v6, v8, v6
	v_lshlrev_b32_e32 v8, 16, v7
	v_mul_f32_e32 v9, 0x3d372713, v8
	v_mul_f32_e32 v9, v9, v8
	v_fma_f32 v9, v9, v8, v8
	v_mul_f32_e32 v9, 0x3f4c422a, v9
	v_mul_f32_e32 v9, -2.0, v9
	v_mul_f32_e32 v9, 0x3fb8aa3b, v9
	v_exp_f32_e32 v9, v9
	v_and_b32_e32 v7, 0xffff0000, v7
	v_add_f32_e32 v9, 1.0, v9
	v_rcp_f32_e32 v9, v9
	s_nop 0
	v_mul_f32_e32 v8, v9, v8
	v_mul_f32_e32 v9, 0x3d372713, v7
	v_mul_f32_e32 v9, v9, v7
	v_fma_f32 v9, v9, v7, v7
	v_mul_f32_e32 v9, 0x3f4c422a, v9
	v_mul_f32_e32 v9, -2.0, v9
	v_mul_f32_e32 v9, 0x3fb8aa3b, v9
	v_exp_f32_e32 v9, v9
	v_mul_f32_e32 v8, v14, v8
	v_add_f32_e32 v9, 1.0, v9
	v_rcp_f32_e32 v9, v9
	s_nop 0
	v_mul_f32_e32 v7, v9, v7
	v_mul_f32_e32 v7, v15, v7
	v_cvt_pk_bf16_f32 v7, v8, v7
	v_add_u32_e32 v8, s23, v52
	v_ashrrev_i32_e32 v9, 31, v8
	v_lshlrev_b64 v[8:9], 12, v[8:9]
	v_lshl_add_u64 v[8:9], s[0:1], 0, v[8:9]
	v_lshl_add_u64 v[8:9], v[8:9], 0, s[30:31]
	v_lshl_add_u64 v[8:9], v[8:9], 0, v[2:3]
	v_add_co_u32_e32 v8, vcc, 0x28000000, v8
	s_nop 1
	v_addc_co_u32_e32 v9, vcc, 0, v9, vcc
	global_store_dwordx4 v[8:9], v[4:7], off offset:1024
	s_barrier
	s_cbranch_scc1 .LBB0_521
